# bundle8 without the peeled first K-iteration (zero64 kept): checks whether peel pays for its code size
# baseline (speedup 1.0000x reference)
.LBB0_287:
	s_add_u32 s4, s26, 0x11c00000
	s_addc_u32 s5, s27, 0
	s_lshl_b32 s6, s6, 5
	s_and_b32 s12, s6, 0x60
	s_mov_b64 s[6:7], 0x80
	s_add_i32 m0, s35, 0x18000
	v_lshl_add_u64 v[8:9], v[8:9], 0, s[6:7]
	s_lshl_b32 s9, s8, 13
	s_lshl_b32 s13, s12, 7
	s_waitcnt vmcnt(2)
	s_barrier
	global_load_lds_dwordx4 v[8:9], off
	v_lshl_add_u64 v[6:7], v[6:7], 0, s[6:7]
	s_add_i32 m0, s35, 0x1a000
	s_add_i32 s64, s35, 0x8000
	s_add_i32 s65, s35, 0xa000
	global_load_lds_dwordx4 v[6:7], off
	v_lshl_add_u64 v[2:3], v[2:3], 0, s[6:7]
	s_mov_b32 m0, s64
	s_add_u32 s10, s42, 0x80080
	global_load_lds_dwordx4 v[2:3], off
	v_lshl_add_u64 v[2:3], v[4:5], 0, s[6:7]
	s_mov_b32 m0, s65
	s_addc_u32 s11, s43, 0
	global_load_lds_dwordx4 v[2:3], off
	s_add_i32 m0, s35, 0x1c000
	s_nop 0
	global_load_lds_dwordx4 v134, s[10:11]
	v_lshl_add_u64 v[2:3], s[10:11], 0, v[130:131]
	s_add_i32 m0, s35, 0x1e000
	s_sext_i32_i16 s73, s2
	global_load_lds_dwordx4 v[2:3], off
	v_and_b32_e32 v1, 15, v0
	v_lshlrev_b32_e32 v2, 1, v13
	v_lshlrev_b32_e32 v3, 2, v0
	v_lshlrev_b32_e32 v4, 6, v0
	s_movk_i32 s2, 0x3c0
	v_lshl_or_b32 v150, s8, 6, v1
	v_lshl_or_b32 v1, v1, 6, v2
	v_and_b32_e32 v3, 32, v3
	v_and_or_b32 v2, v4, s2, v2
	v_bitop3_b32 v151, s13, v2, v3 bitop3:0xf6
	v_lshlrev_b32_e32 v2, 9, v0
	v_bitop3_b32 v1, v1, s9, v3 bitop3:0xde
	v_and_b32_e32 v2, 0x30000, v2
	v_lshlrev_b32_e32 v3, 12, v14
	v_or3_b32 v2, v11, v2, v3
	v_add_u32_e32 v138, v2, v12
	v_lshlrev_b32_e32 v2, 5, v10
	s_waitcnt vmcnt(6)
	s_cmpk_lt_u32 s3, 0x100
	v_and_b32_e32 v2, 0x70000, v2
	s_cselect_b64 s[8:9], -1, 0
	v_or3_b32 v2, v11, v2, v3
	s_add_i32 s70, 0, 0x10000
	s_add_i32 s71, 0, 0x14000
	s_mov_b32 s66, 0
	s_ashr_i32 s67, s33, 31
	v_or_b32_e32 v152, s12, v13
	v_mov_b32_e32 v139, v135
	v_add_u32_e32 v140, v2, v12
	v_mov_b32_e32 v141, v135
	v_mov_b64_e32 v[142:143], 0x1600
	v_mov_b64_e32 v[144:145], 0x15ff
	v_add_u32_e32 v153, s70, v151
	v_add_u32_e32 v154, s71, v151
	v_add_u32_e32 v155, 0, v1
	s_movk_i32 s72, 0x2c00
	s_barrier
	s_branch .LBB0_290

.LBB0_365:
	s_add_u32 s14, s26, 0x8000000
	s_addc_u32 s15, s27, 0
	s_lshl_b32 s70, s2, 6
	s_lshl_b32 s5, s2, 13
	s_lshl_b32 s2, s3, 5
	s_mov_b64 s[16:17], 0x80
	s_and_b32 s10, s2, 0x60
	s_add_i32 m0, s31, 0x18000
	v_lshl_add_u64 v[8:9], v[8:9], 0, s[16:17]
	s_lshl_b32 s6, s10, 7
	s_waitcnt vmcnt(2)
	s_barrier
	global_load_lds_dwordx4 v[8:9], off
	v_lshl_add_u64 v[6:7], v[6:7], 0, s[16:17]
	s_add_i32 m0, s31, 0x1a000
	s_add_i32 s71, s31, 0x8000
	s_add_i32 s72, s31, 0xa000
	global_load_lds_dwordx4 v[6:7], off
	v_lshl_add_u64 v[2:3], v[2:3], 0, s[16:17]
	s_mov_b32 m0, s71
	s_add_u32 s2, s56, 0x160080
	global_load_lds_dwordx4 v[2:3], off
	v_lshl_add_u64 v[2:3], v[4:5], 0, s[16:17]
	s_mov_b32 m0, s72
	s_addc_u32 s3, s57, 0
	global_load_lds_dwordx4 v[2:3], off
	s_add_i32 m0, s31, 0x1c000
	s_nop 0
	global_load_lds_dwordx4 v182, s[2:3]
	v_lshl_add_u64 v[2:3], s[2:3], 0, v[186:187]
	s_add_i32 m0, s31, 0x1e000
	v_bfe_u32 v1, v0, 4, 2
	global_load_lds_dwordx4 v[2:3], off
	v_and_b32_e32 v179, 15, v0
	v_lshlrev_b32_e32 v2, 4, v1
	v_lshlrev_b32_e32 v4, 2, v0
	v_lshlrev_b32_e32 v5, 6, v0
	s_movk_i32 s2, 0x3c0
	v_lshl_or_b32 v3, v179, 6, v2
	v_and_b32_e32 v4, 32, v4
	v_and_or_b32 v2, v5, s2, v2
	s_cmpk_lt_u32 s4, 0x100
	v_bitop3_b32 v3, v3, s5, v4 bitop3:0xde
	v_bitop3_b32 v206, s6, v2, v4 bitop3:0xf6
	s_cselect_b64 s[34:35], -1, 0
	v_cmp_eq_u32_e64 s[2:3], 0, v1
	v_cmp_eq_u32_e64 s[4:5], 1, v1
	v_cmp_eq_u32_e64 s[6:7], 2, v1
	v_cmp_eq_u32_e64 s[8:9], 3, v1
	s_ashr_i32 s73, s33, 31
	s_ashr_i32 s74, s18, 31
	v_lshl_or_b32 v207, v1, 3, s10
	v_add_u16_e32 v1, v10, v11
	s_waitcnt vmcnt(6)
	s_cmp_lg_u64 s[26:27], 0
	v_lshrrev_b16_e32 v1, 1, v1
	s_cselect_b64 s[40:41], -1, 0
	v_add_lshl_u32 v188, v12, v1, 1
	v_add_lshl_u32 v190, v13, v1, 1
	s_add_i32 s75, 0, 0x10000
	s_add_i32 s76, 0, 0x14000
	v_mbcnt_lo_u32_b32 v1, -1, 0
	v_mov_b32_e32 v189, v183
	v_mov_b32_e32 v191, v183
	v_mov_b64_e32 v[192:193], 0x400
	v_mov_b64_e32 v[194:195], 0x3ff
	v_add_u32_e32 v208, s75, v206
	v_add_u32_e32 v209, s76, v206
	v_add_u32_e32 v210, 0, v3
	v_mbcnt_hi_u32_b32 v211, -1, v1
	s_barrier
	s_branch .LBB0_368

.LBB0_691:
	s_add_u32 s2, s26, 0x11000000
	s_addc_u32 s3, s27, 0
	s_lshl_b32 s4, s4, 5
	s_and_b32 s12, s4, 0x60
	s_mov_b64 s[4:5], 0x80
	s_add_i32 m0, s53, 0x18000
	v_lshl_add_u64 v[8:9], v[8:9], 0, s[4:5]
	s_lshl_b32 s9, s8, 13
	s_waitcnt vmcnt(2)
	s_barrier
	global_load_lds_dwordx4 v[8:9], off
	v_lshl_add_u64 v[6:7], v[6:7], 0, s[4:5]
	s_add_i32 m0, s53, 0x1a000
	s_add_i32 s65, s53, 0x8000
	s_add_i32 s66, s53, 0xa000
	global_load_lds_dwordx4 v[6:7], off
	v_lshl_add_u64 v[2:3], v[2:3], 0, s[4:5]
	s_mov_b32 m0, s65
	s_add_u32 s10, s56, 0x80080
	global_load_lds_dwordx4 v[2:3], off
	v_lshl_add_u64 v[2:3], v[4:5], 0, s[4:5]
	s_mov_b32 m0, s66
	s_addc_u32 s11, s57, 0
	global_load_lds_dwordx4 v[2:3], off
	s_add_i32 m0, s53, 0x1c000
	s_nop 0
	global_load_lds_dwordx4 v152, s[10:11]
	v_lshl_add_u64 v[2:3], s[10:11], 0, v[156:157]
	s_add_i32 m0, s53, 0x1e000
	v_lshl_or_b32 v1, v189, 6, v137
	global_load_lds_dwordx4 v[2:3], off
	v_lshlrev_b32_e32 v2, 2, v189
	v_and_b32_e32 v2, 32, v2
	v_bitop3_b32 v1, v1, s9, v2 bitop3:0xde
	v_lshlrev_b32_e32 v2, 9, v0
	v_and_b32_e32 v2, 0x30000, v2
	v_lshlrev_b32_e32 v3, 12, v186
	v_or3_b32 v2, v184, v2, v3
	v_add_u32_e32 v130, v2, v185
	v_lshlrev_b32_e32 v2, 5, v188
	s_waitcnt vmcnt(6)
	s_cmpk_lt_u32 s7, 0x100
	v_and_b32_e32 v2, 0x70000, v2
	s_sext_i32_i8 s74, s6
	v_lshl_or_b32 v139, s12, 7, v136
	s_cselect_b64 s[6:7], -1, 0
	v_or3_b32 v2, v184, v2, v3
	s_add_i32 s68, 0, 0x10000
	s_add_i32 s69, 0, 0x14000
	v_lshl_or_b32 v138, s8, 6, v189
	s_ashr_i32 s67, s33, 31
	v_or_b32_e32 v140, s12, v187
	v_mov_b32_e32 v131, v153
	v_add_u32_e32 v132, v2, v185
	v_mov_b32_e32 v133, v153
	v_add_u32_e32 v141, s68, v139
	v_add_u32_e32 v142, s69, v139
	v_add_u32_e32 v143, 0, v1
	s_mov_b64 s[8:9], 0x20000
	s_mov_b32 s70, 0x20000
	s_mov_b64 s[10:11], 0x24000
	s_mov_b32 s71, 0x24000
	s_mov_b64 s[12:13], 0x28000
	s_mov_b32 s72, 0x28000
	s_mov_b64 s[14:15], 0x2c000
	s_mov_b32 s73, 0x2c000
	s_barrier
	s_branch .LBB0_694

.LBB0_715:
	s_add_u32 s2, s26, 0x11400000
	s_addc_u32 s3, s27, 0
	s_lshl_b32 s4, s4, 5
	s_and_b32 s12, s4, 0x60
	s_mov_b64 s[4:5], 0x80
	s_add_i32 m0, s53, 0x18000
	v_lshl_add_u64 v[8:9], v[8:9], 0, s[4:5]
	s_lshl_b32 s9, s8, 13
	s_waitcnt vmcnt(2)
	s_barrier
	global_load_lds_dwordx4 v[8:9], off
	v_lshl_add_u64 v[6:7], v[6:7], 0, s[4:5]
	s_add_i32 m0, s53, 0x1a000
	s_add_i32 s66, s53, 0x8000
	s_add_i32 s67, s53, 0xa000
	global_load_lds_dwordx4 v[6:7], off
	v_lshl_add_u64 v[2:3], v[2:3], 0, s[4:5]
	s_mov_b32 m0, s66
	s_add_u32 s10, s56, 0x80080
	global_load_lds_dwordx4 v[2:3], off
	v_lshl_add_u64 v[2:3], v[4:5], 0, s[4:5]
	s_mov_b32 m0, s67
	s_addc_u32 s11, s57, 0
	global_load_lds_dwordx4 v[2:3], off
	s_add_i32 m0, s53, 0x1c000
	s_nop 0
	global_load_lds_dwordx4 v152, s[10:11]
	v_lshl_add_u64 v[2:3], s[10:11], 0, v[156:157]
	s_add_i32 m0, s53, 0x1e000
	v_lshl_or_b32 v1, v189, 6, v137
	global_load_lds_dwordx4 v[2:3], off
	v_lshlrev_b32_e32 v2, 2, v189
	v_and_b32_e32 v2, 32, v2
	v_bitop3_b32 v1, v1, s9, v2 bitop3:0xde
	v_lshlrev_b32_e32 v2, 9, v0
	v_and_b32_e32 v2, 0x30000, v2
	v_lshlrev_b32_e32 v3, 12, v186
	v_or3_b32 v2, v184, v2, v3
	v_add_u32_e32 v130, v2, v185
	v_lshlrev_b32_e32 v2, 5, v188
	s_waitcnt vmcnt(6)
	s_cmpk_lt_u32 s7, 0x100
	v_and_b32_e32 v2, 0x70000, v2
	s_sext_i32_i8 s75, s6
	v_lshl_or_b32 v136, s12, 7, v136
	s_cselect_b64 s[6:7], -1, 0
	v_or3_b32 v2, v184, v2, v3
	s_add_i32 s69, 0, 0x10000
	s_add_i32 s70, 0, 0x14000
	v_lshl_or_b32 v138, s8, 6, v189
	s_ashr_i32 s68, s33, 31
	v_or_b32_e32 v137, s12, v187
	v_mov_b32_e32 v131, v153
	v_add_u32_e32 v132, v2, v185
	v_mov_b32_e32 v133, v153
	v_add_u32_e32 v139, s69, v136
	v_add_u32_e32 v140, s70, v136
	v_add_u32_e32 v141, 0, v1
	s_mov_b64 s[8:9], 0x100000
	s_mov_b32 s71, 0x100000
	s_mov_b64 s[10:11], 0x120000
	s_mov_b32 s72, 0x120000
	s_mov_b64 s[12:13], 0x140000
	s_mov_b32 s73, 0x140000
	s_mov_b64 s[14:15], 0x160000
	s_mov_b32 s74, 0x160000
	s_barrier
	s_branch .LBB0_718

.LBB0_1398:
	s_add_u32 s12, s26, 0x8000000
	s_addc_u32 s13, s27, 0
	s_add_u32 s14, s26, 0x27c00000
	s_addc_u32 s15, s27, 0
	s_add_u32 s16, s26, 0x40000
	s_addc_u32 s17, s27, 0
	s_lshl_b32 s59, s4, 6
	s_lshl_b32 s6, s4, 13
	s_lshl_b32 s4, s5, 5
	s_mov_b64 s[30:31], 0x80
	s_and_b32 s10, s4, 0x60
	s_add_i32 m0, s45, 0x18000
	v_lshl_add_u64 v[8:9], v[8:9], 0, s[30:31]
	s_lshl_b32 s7, s10, 7
	s_waitcnt vmcnt(2)
	s_barrier
	global_load_lds_dwordx4 v[8:9], off
	v_lshl_add_u64 v[6:7], v[6:7], 0, s[30:31]
	s_add_i32 m0, s45, 0x1a000
	s_add_i32 s60, s45, 0x8000
	s_add_i32 s61, s45, 0xa000
	global_load_lds_dwordx4 v[6:7], off
	v_lshl_add_u64 v[2:3], v[2:3], 0, s[30:31]
	s_mov_b32 m0, s60
	s_add_u32 s4, s48, 0x80080
	global_load_lds_dwordx4 v[2:3], off
	v_lshl_add_u64 v[2:3], v[4:5], 0, s[30:31]
	s_mov_b32 m0, s61
	s_addc_u32 s5, s49, 0
	global_load_lds_dwordx4 v[2:3], off
	s_add_i32 m0, s45, 0x1c000
	s_nop 0
	global_load_lds_dwordx4 v148, s[4:5]
	v_lshl_add_u64 v[2:3], s[4:5], 0, v[152:153]
	s_add_i32 m0, s45, 0x1e000
	v_bfe_u32 v1, v0, 4, 2
	global_load_lds_dwordx4 v[2:3], off
	s_sext_i32_i8 s65, s2
	v_and_b32_e32 v180, 15, v0
	v_lshlrev_b32_e32 v2, 4, v1
	v_lshlrev_b32_e32 v4, 2, v0
	v_lshlrev_b32_e32 v5, 6, v0
	s_movk_i32 s2, 0x3c0
	v_lshl_or_b32 v3, v180, 6, v2
	v_and_b32_e32 v4, 32, v4
	v_and_or_b32 v2, v5, s2, v2
	v_bitop3_b32 v3, v3, s6, v4 bitop3:0xde
	v_bitop3_b32 v181, s7, v2, v4 bitop3:0xf6
	s_cmpk_lt_u32 s3, 0x100
	v_cmp_eq_u32_e64 s[2:3], 0, v1
	v_cmp_eq_u32_e64 s[4:5], 1, v1
	v_cmp_eq_u32_e64 s[6:7], 2, v1
	v_cmp_eq_u32_e64 s[8:9], 3, v1
	v_lshl_or_b32 v182, v1, 3, s10
	v_lshlrev_b32_e32 v1, 9, v0
	v_and_b32_e32 v1, 0x30000, v1
	v_lshlrev_b32_e32 v2, 12, v12
	v_or3_b32 v1, v10, v1, v2
	v_add_u32_e32 v154, v1, v11
	v_lshlrev_b32_e32 v1, 5, v13
	v_and_b32_e32 v1, 0x70000, v1
	s_waitcnt vmcnt(6)
	v_or3_b32 v1, v10, v1, v2
	s_cselect_b64 s[34:35], -1, 0
	v_add_u32_e32 v156, v1, v11
	s_add_i32 s63, 0, 0x10000
	s_add_i32 s64, 0, 0x14000
	v_mbcnt_lo_u32_b32 v1, -1, 0
	s_ashr_i32 s62, s33, 31
	v_mov_b32_e32 v155, v149
	v_mov_b32_e32 v157, v149
	v_mov_b64_e32 v[158:159], 0x400
	v_mov_b64_e32 v[160:161], 0x3ff
	v_add_u32_e32 v183, s63, v181
	v_add_u32_e32 v184, s64, v181
	v_add_u32_e32 v185, 0, v3
	v_mbcnt_hi_u32_b32 v186, -1, v1
	s_barrier
	s_branch .LBB0_1401

.LBB0_1473:
	s_add_u32 s14, s26, 0x11c00000
	s_addc_u32 s15, s27, 0
	s_add_u32 s16, s26, 0x40000
	s_addc_u32 s17, s27, 0
	s_lshl_b32 s7, s7, 5
	s_mov_b64 s[30:31], 0x80
	s_and_b32 s7, s7, 0x60
	s_add_i32 m0, s44, 0x18000
	v_lshl_add_u64 v[8:9], v[8:9], 0, s[30:31]
	s_lshl_b32 s11, s6, 13
	s_lshl_b32 s34, s7, 7
	s_waitcnt vmcnt(2)
	s_barrier
	global_load_lds_dwordx4 v[8:9], off
	v_lshl_add_u64 v[6:7], v[6:7], 0, s[30:31]
	s_add_i32 m0, s44, 0x1a000
	s_add_i32 s48, s44, 0x8000
	s_add_i32 s49, s44, 0xa000
	global_load_lds_dwordx4 v[6:7], off
	v_lshl_add_u64 v[2:3], v[2:3], 0, s[30:31]
	s_mov_b32 m0, s48
	s_add_u32 s8, s4, 0x80080
	global_load_lds_dwordx4 v[2:3], off
	v_lshl_add_u64 v[2:3], v[4:5], 0, s[30:31]
	s_mov_b32 m0, s49
	s_addc_u32 s9, s5, 0
	global_load_lds_dwordx4 v[2:3], off
	s_add_i32 m0, s44, 0x1c000
	s_nop 0
	global_load_lds_dwordx4 v142, s[8:9]
	v_lshl_add_u64 v[2:3], s[8:9], 0, v[138:139]
	s_add_i32 m0, s44, 0x1e000
	s_sext_i32_i16 s59, s2
	global_load_lds_dwordx4 v[2:3], off
	v_and_b32_e32 v2, 15, v0
	v_lshlrev_b32_e32 v3, 1, v13
	v_lshlrev_b32_e32 v4, 2, v0
	v_lshlrev_b32_e32 v5, 6, v0
	s_movk_i32 s2, 0x3c0
	v_lshl_or_b32 v1, s6, 6, v2
	v_lshl_or_b32 v2, v2, 6, v3
	v_and_b32_e32 v4, 32, v4
	v_and_or_b32 v3, v5, s2, v3
	v_bitop3_b32 v163, s34, v3, v4 bitop3:0xf6
	v_lshlrev_b32_e32 v3, 9, v0
	v_bitop3_b32 v2, v2, s11, v4 bitop3:0xde
	v_and_b32_e32 v3, 0x30000, v3
	v_lshlrev_b32_e32 v4, 12, v14
	v_or3_b32 v3, v11, v3, v4
	v_add_u32_e32 v146, v3, v12
	v_lshlrev_b32_e32 v3, 5, v10
	s_waitcnt vmcnt(6)
	s_cmpk_lt_u32 s3, 0x100
	v_and_b32_e32 v3, 0x70000, v3
	v_mov_b32_e32 v154, 1.0
	s_cselect_b64 s[34:35], -1, 0
	v_or3_b32 v3, v11, v3, v4
	v_mov_b32_e32 v155, v154
	s_add_i32 s54, 0, 0x10000
	s_add_i32 s55, 0, 0x14000
	s_mov_b32 s52, 0
	s_ashr_i32 s53, s33, 31
	v_or_b32_e32 v165, s7, v13
	v_mov_b32_e32 v147, v143
	v_add_u32_e32 v148, v3, v12
	v_mov_b32_e32 v149, v143
	s_mov_b32 s8, -1
	v_mov_b64_e32 v[150:151], 0x1600
	v_mov_b64_e32 v[152:153], 0x15ff
	v_add_u32_e32 v174, s54, v163
	v_add_u32_e32 v175, s55, v163
	v_add_u32_e32 v176, 0, v2
	v_mov_b32_e32 v177, 0x358637bd
	s_mov_b32 s56, 0xf800000
	v_mov_b32_e32 v178, 0x260
	s_movk_i32 s57, 0x2c00
	v_mov_b64_e32 v[156:157], v[154:155]
	v_mov_b32_e32 v66, v154
	v_mov_b32_e32 v67, v154
	v_mov_b32_e32 v179, v154
	v_mov_b32_e32 v180, v154
	s_barrier
	s_branch .LBB0_1476

.LBB0_1552:
	s_add_u32 s6, s26, 0x27c00000
	s_addc_u32 s7, s27, 0
	s_lshl_b32 s5, s5, 5
	s_mov_b64 s[8:9], 0x80
	s_and_b32 s5, s5, 0x60
	s_add_i32 m0, s30, 0x18000
	v_lshl_add_u64 v[8:9], v[8:9], 0, s[8:9]
	s_lshl_b32 s12, s3, 13
	s_lshl_b32 s13, s5, 7
	s_waitcnt vmcnt(2)
	s_barrier
	global_load_lds_dwordx4 v[8:9], off
	v_lshl_add_u64 v[6:7], v[6:7], 0, s[8:9]
	s_add_i32 m0, s30, 0x1a000
	s_add_i32 s37, s30, 0x8000
	s_add_i32 s38, s30, 0xa000
	global_load_lds_dwordx4 v[6:7], off
	v_lshl_add_u64 v[2:3], v[2:3], 0, s[8:9]
	s_mov_b32 m0, s37
	s_add_u32 s10, s20, 0x160080
	global_load_lds_dwordx4 v[2:3], off
	v_lshl_add_u64 v[2:3], v[4:5], 0, s[8:9]
	s_mov_b32 m0, s38
	s_addc_u32 s11, s21, 0
	global_load_lds_dwordx4 v[2:3], off
	s_add_i32 m0, s30, 0x1c000
	s_nop 0
	global_load_lds_dwordx4 v130, s[10:11]
	v_lshl_add_u64 v[2:3], s[10:11], 0, v[134:135]
	s_add_i32 m0, s30, 0x1e000
	v_lshlrev_b32_e32 v5, 2, v0
	global_load_lds_dwordx4 v[2:3], off
	v_bfe_u32 v2, v0, 4, 2
	v_and_b32_e32 v3, 15, v0
	v_lshl_or_b32 v148, s3, 6, v3
	v_lshlrev_b32_e32 v4, 4, v2
	v_lshlrev_b32_e32 v0, 6, v0
	s_movk_i32 s3, 0x3c0
	s_cmpk_lt_u32 s2, 0x100
	v_and_b32_e32 v5, 32, v5
	v_and_or_b32 v0, v0, s3, v4
	s_cselect_b64 s[10:11], -1, 0
	s_ashr_i32 s39, s33, 31
	v_lshl_or_b32 v3, v3, 6, v4
	v_bitop3_b32 v149, s13, v0, v5 bitop3:0xf6
	s_waitcnt vmcnt(6)
	s_cmp_lg_u64 s[50:51], 0
	v_add_u16_e32 v0, v1, v10
	v_bitop3_b32 v3, v3, s12, v5 bitop3:0xde
	s_cselect_b64 s[12:13], -1, 0
	v_lshrrev_b16_e32 v0, 1, v0
	s_add_i32 s40, 0, 0x10000
	s_add_i32 s41, 0, 0x14000
	s_sext_i32_i8 s45, s4
	v_lshl_or_b32 v150, v2, 3, s5
	v_add_lshl_u32 v136, v11, v0, 1
	v_mov_b32_e32 v137, v131
	v_add_lshl_u32 v138, v12, v0, 1
	v_mov_b32_e32 v139, v131
	v_mov_b64_e32 v[140:141], 0x400
	v_mov_b64_e32 v[142:143], 0x3ff
	v_add_u32_e32 v151, s40, v149
	v_add_u32_e32 v152, s41, v149
	v_add_u32_e32 v153, 0, v3
	s_barrier
	s_branch .LBB0_1555
